# diff tile-skip rule: own-key score bound from the two diagonal tiles' key norms (2 readlanes) instead of the maximum over all 64 tiles (6 shuffle rounds)
# speedup vs baseline: 1.0073x; 1.0073x over previous
; #define LAS __attribute__((address_space(3)))
; __device__ __forceinline__ void diff_unit(const PolDiff& P, LAS unsigned char* lds, const Ptrs& X) {
;     ...
;       float qm1 = 0.f, qm2 = 0.f;
; #pragma unroll
;       for (int w_ = 0; w_ < 4; ++w_) { qm1 = fmaxf(qm1, ((LAS float*)(lds + DF_SCR))[w_ * 64]); qm2 = fmaxf(qm2, ((LAS float*)(lds + DF_SCR))[(w_ + 4) * 64]); }
;       qm1 = sqrtf(qm1) * 1.01f; qm2 = sqrtf(qm2) * 1.01f;
;       const float* kn = X.kn + ((P.b * 8 + P.h) * 2) * 128;
;       const float k1_ = sqrtf(kn[2 * lane] + kn[2 * lane + 1]) * 1.001f, k2_ = sqrtf(kn[128 + 2 * lane] + kn[128 + 2 * lane + 1]) * 1.001f;
;       const float sb = fmaxf(qm1 * k1_, qm2 * k2_);
;       const int i0u = 128 * P.qb;
;       const int dist = lane < 2 * P.qb ? i0u - (64 * lane + 63) : (lane > 2 * P.qb + 1 ? 64 * lane - (i0u + 127) : 0);
;       const bool visit = sb + P.nsl * (float)dist > -152.f;
;       const unsigned long long mask = __ballot(visit) | (3ull << (2 * P.qb));
;       int lo = __builtin_ctzll(mask), hi_t = 63 - __builtin_clzll(mask);
;     ...
;       if (hi_t - lo + 1 < 4) { if (lo > 1) lo -= 2; else hi_t += 2; }
.LBB0_255:
	s_or_b64 exec, exec, s[0:1]
	s_add_i32 s0, 0, 0x18000
	v_mov_b32_e32 v2, s0
	v_readlane_b32 s0, v254, 9
	s_waitcnt lgkmcnt(0)
	s_barrier
	ds_read_b32 v11, v2
	v_mov_b32_e32 v2, s0
	v_readlane_b32 s0, v254, 10
	ds_read_b32 v9, v2
	s_lshl_b32 s1, s2, 13
	v_mov_b32_e32 v2, s0
	v_readlane_b32 s0, v254, 11
	ds_read_b32 v13, v2
	v_lshlrev_b32_e32 v19, 3, v8
	v_mov_b32_e32 v2, s0
	v_readlane_b32 s0, v254, 12
	ds_read_b32 v10, v2
	v_lshlrev_b32_e32 v20, 6, v8
	v_mov_b32_e32 v2, s0
	v_readlane_b32 s0, v254, 13
	ds_read_b32 v14, v2
	s_nop 0
	v_mov_b32_e32 v2, s0
	v_readlane_b32 s0, v254, 14
	ds_read_b32 v12, v2
	s_nop 0
	v_mov_b32_e32 v2, s0
	v_readlane_b32 s0, v254, 15
	ds_read_b32 v16, v2
	s_nop 0
	v_mov_b32_e32 v2, s0
	s_lshl_b32 s0, s5, 10
	s_or_b32 s0, s1, s0
	s_add_u32 s0, s62, s0
	s_addc_u32 s1, s63, 0
	ds_read_b32 v15, v2
	global_load_dwordx2 v[4:5], v19, s[0:1]
	global_load_dwordx2 v[2:3], v19, s[0:1] offset:512
	s_lshl_b32 s29, s4, 1
	v_cmp_le_u32_e32 vcc, s29, v8
	s_and_saveexec_b64 s[0:1], vcc
	s_xor_b64 s[0:1], exec, s[0:1]
	s_or_b32 s4, s29, 1
	v_subrev_u32_e32 v17, s42, v20
	v_add_u32_e32 v17, 0xffffff81, v17
	v_cmp_lt_u32_e32 vcc, s4, v8
	s_nop 1
	v_cndmask_b32_e32 v17, 0, v17, vcc
	s_andn2_saveexec_b64 s[0:1], s[0:1]
	v_sub_u32_e32 v17, s42, v20
	v_subrev_u32_e32 v17, 63, v17
	s_or_b64 exec, exec, s[0:1]
	s_waitcnt lgkmcnt(5)
	v_max3_f32 v11, v11, 0, v13
	s_waitcnt lgkmcnt(1)
	v_max3_f32 v11, v11, v14, v16
	s_mov_b32 s0, 0xf800000
	v_mul_f32_e32 v13, 0x4f800000, v11
	v_cmp_gt_f32_e32 vcc, s0, v11
	v_max3_f32 v9, v9, 0, v10
	s_waitcnt lgkmcnt(0)
	v_max3_f32 v9, v9, v12, v15
	v_cndmask_b32_e32 v11, v11, v13, vcc
	v_sqrt_f32_e32 v13, v11
	s_waitcnt vmcnt(1)
	v_add_f32_e32 v4, v4, v5
	v_mul_f32_e32 v5, 0x4f800000, v4
	s_waitcnt vmcnt(0)
	v_add_f32_e32 v2, v2, v3
	v_add_u32_e32 v10, -1, v13
	v_fma_f32 v12, -v10, v13, v11
	v_cmp_ge_f32_e64 s[4:5], 0, v12
	v_add_u32_e32 v12, 1, v13
	v_mul_f32_e32 v3, 0x4f800000, v2
	v_cndmask_b32_e64 v10, v13, v10, s[4:5]
	v_fma_f32 v13, -v12, v13, v11
	v_cmp_lt_f32_e64 s[4:5], 0, v13
	s_nop 1
	v_cndmask_b32_e64 v10, v10, v12, s[4:5]
	v_mul_f32_e32 v12, 0x37800000, v10
	v_cndmask_b32_e32 v10, v10, v12, vcc
	v_mul_f32_e32 v12, 0x4f800000, v9
	v_cmp_gt_f32_e32 vcc, s0, v9
	v_cmp_class_f32_e64 s[4:5], v11, v216
	s_nop 0
	v_cndmask_b32_e32 v9, v9, v12, vcc
	v_sqrt_f32_e32 v12, v9
	v_cndmask_b32_e64 v10, v10, v11, s[4:5]
	v_mul_f32_e32 v10, 0x3f8147ae, v10
	v_add_u32_e32 v11, -1, v12
	v_fma_f32 v13, -v11, v12, v9
	v_cmp_ge_f32_e64 s[4:5], 0, v13
	v_add_u32_e32 v13, 1, v12
	s_nop 0
	v_cndmask_b32_e64 v11, v12, v11, s[4:5]
	v_fma_f32 v12, -v13, v12, v9
	v_cmp_lt_f32_e64 s[4:5], 0, v12
	s_nop 1
	v_cndmask_b32_e64 v11, v11, v13, s[4:5]
	v_mul_f32_e32 v12, 0x37800000, v11
	v_cndmask_b32_e32 v11, v11, v12, vcc
	v_cmp_gt_f32_e32 vcc, s0, v4
	v_cmp_class_f32_e64 s[4:5], v9, v216
	s_nop 0
	v_cndmask_b32_e32 v4, v4, v5, vcc
	v_sqrt_f32_e32 v5, v4
	v_cndmask_b32_e64 v9, v11, v9, s[4:5]
	v_mul_f32_e32 v9, 0x3f8147ae, v9
	v_add_u32_e32 v11, -1, v5
	v_fma_f32 v12, -v11, v5, v4
	v_cmp_ge_f32_e64 s[4:5], 0, v12
	v_add_u32_e32 v12, 1, v5
	s_nop 0
	v_cndmask_b32_e64 v11, v5, v11, s[4:5]
	v_fma_f32 v5, -v12, v5, v4
	v_cmp_lt_f32_e64 s[4:5], 0, v5
	s_nop 1
	v_cndmask_b32_e64 v5, v11, v12, s[4:5]
	v_mul_f32_e32 v11, 0x37800000, v5
	v_cndmask_b32_e32 v5, v5, v11, vcc
	v_cmp_gt_f32_e32 vcc, s0, v2
	v_cmp_class_f32_e64 s[4:5], v4, v216
	s_sub_i32 s0, 8, s11
	v_cndmask_b32_e32 v2, v2, v3, vcc
	v_sqrt_f32_e32 v3, v2
	v_cndmask_b32_e64 v4, v5, v4, s[4:5]
	v_mul_f32_e32 v4, 0x3f8020c5, v4
	v_add_u32_e32 v5, -1, v3
	v_fma_f32 v11, -v5, v3, v2
	v_cmp_ge_f32_e64 s[4:5], 0, v11
	v_add_u32_e32 v11, 1, v3
	s_nop 0
	v_cndmask_b32_e64 v5, v3, v5, s[4:5]
	v_fma_f32 v3, -v11, v3, v2
	v_cmp_lt_f32_e64 s[4:5], 0, v3
	s_nop 1
	v_cndmask_b32_e64 v3, v5, v11, s[4:5]
	v_mul_f32_e32 v5, 0x37800000, v3
	v_cndmask_b32_e32 v3, v3, v5, vcc
	v_cmp_class_f32_e32 vcc, v2, v216
	v_cvt_f32_i32_e32 v5, v17
	s_nop 0
	v_cndmask_b32_e32 v2, v3, v2, vcc
	v_mul_f32_e32 v3, v10, v4
	v_cvt_f32_ubyte0_e32 v4, s0
	v_exp_f32_e64 v4, -v4
	v_mul_f32_e32 v2, 0x3f8020c5, v2
	v_mul_f32_e32 v2, v9, v2
	v_max_f32_e32 v2, v3, v2
	s_add_i32 s4, s29, 1
	s_nop 3
	v_readlane_b32 s98, v2, s29
	v_readlane_b32 s99, v2, s4
	s_nop 3
	v_mov_b32_e32 v20, s98
	v_max_f32_e32 v20, s99, v20
	v_sub_f32_e32 v20, 0xc2400000, v20
	v_max_f32_e32 v20, 0xc3180000, v20
	v_mul_f32_e32 v200, 0xbfb8aa3b, v4
	v_fmac_f32_e32 v2, v200, v5
	v_cmp_lt_f32_e32 vcc, v20, v2
	s_lshl_b64 s[0:1], 3, s29
	s_or_b64 s[0:1], vcc, s[0:1]
	s_ff1_i32_b64 s4, s[0:1]
	s_flbit_i32_b64 s12, s[0:1]
	s_xor_b32 s11, s12, 63
	s_add_i32 s0, s12, s4
	s_bitcmp0_b32 s0, 0
	s_cbranch_scc1 .LBB0_263
	s_mov_b32 s5, s27
	s_cmp_eq_u64 s[4:5], 0
	s_cbranch_scc1 .LBB0_310
	s_add_i32 s4, s4, -1
	s_cbranch_execnz .LBB0_263
